# v094 + in-projection epilogue: the eight dead accumulator copies are skipped on the gelu path
# baseline (speedup 1.0000x reference)
.LBB0_242:
	s_and_b32 s33, s14, 1
	s_cmp_lg_u32 s6, 2
	s_cselect_b64 s[14:15], -1, 0
	s_cmp_eq_u32 s6, 4
	v_cndmask_b32_e64 v159, 0, 1, s[14:15]
	s_cselect_b64 s[76:77], -1, 0
	s_lshl_b32 s69, s33, 2
	s_waitcnt lgkmcnt(0)
	v_pk_mul_f32 v[144:145], v[144:145], v[160:161] op_sel_hi:[1,0]
	v_pk_mul_f32 v[146:147], v[146:147], v[160:161] op_sel_hi:[1,0]
	v_pk_mul_f32 v[140:141], v[140:141], v[160:161] op_sel_hi:[1,0]
	v_pk_mul_f32 v[142:143], v[142:143], v[160:161] op_sel_hi:[1,0]
	v_pk_mul_f32 v[136:137], v[136:137], v[160:161] op_sel_hi:[1,0]
	v_pk_mul_f32 v[138:139], v[138:139], v[160:161] op_sel_hi:[1,0]
	v_pk_mul_f32 v[132:133], v[132:133], v[160:161] op_sel_hi:[1,0]
	v_pk_mul_f32 v[134:135], v[134:135], v[160:161] op_sel_hi:[1,0]
	s_mov_b64 s[16:17], -1
	s_and_b64 vcc, exec, s[78:79]
	v_cmp_ne_u32_e64 s[14:15], 1, v159
	s_cbranch_vccz .LBB0_249
	s_and_b64 vcc, exec, s[14:15]
	s_cbranch_vccz .Lp1_gelu_1
	v_mov_b64_e32 v[160:161], v[144:145]
	v_mov_b64_e32 v[162:163], v[146:147]
	v_mov_b64_e32 v[164:165], v[140:141]
	v_mov_b64_e32 v[174:175], v[142:143]
	v_mov_b64_e32 v[176:177], v[136:137]
	v_mov_b64_e32 v[178:179], v[138:139]
	v_mov_b64_e32 v[180:181], v[132:133]
	v_mov_b64_e32 v[182:183], v[134:135]
	s_branch .LBB0_248
.Lp1_gelu_1:
	v_mul_f32_e32 v159, 0x3d922279, v144
	v_fmaak_f32 v159, v144, v159, 0x3fcc422a
	v_mul_f32_e32 v160, 0x3d922279, v145
	v_mul_f32_e32 v159, v144, v159
	v_fmaak_f32 v160, v145, v160, 0x3fcc422a
	v_mul_f32_e32 v159, 0xbfb8aa3b, v159
	v_mul_f32_e32 v160, v145, v160
	v_exp_f32_e32 v159, v159
	v_mul_f32_e32 v160, 0xbfb8aa3b, v160
	v_exp_f32_e32 v161, v160
	v_mul_f32_e32 v162, 0x3d922279, v147
	v_add_f32_e32 v159, 1.0, v159
	v_rcp_f32_e32 v160, v159
	v_add_f32_e32 v159, 1.0, v161
	v_rcp_f32_e32 v161, v159
	v_mul_f32_e32 v159, 0x3d922279, v146
	v_fmaak_f32 v159, v146, v159, 0x3fcc422a
	v_mul_f32_e32 v159, v146, v159
	v_fmaak_f32 v162, v147, v162, 0x3fcc422a
	v_mul_f32_e32 v159, 0xbfb8aa3b, v159
	v_mul_f32_e32 v162, v147, v162
	v_exp_f32_e32 v159, v159
	v_mul_f32_e32 v162, 0xbfb8aa3b, v162
	v_exp_f32_e32 v163, v162
	v_mul_f32_e32 v164, 0x3d922279, v141
	v_add_f32_e32 v159, 1.0, v159
	v_rcp_f32_e32 v162, v159
	v_add_f32_e32 v159, 1.0, v163
	v_rcp_f32_e32 v163, v159
	v_mul_f32_e32 v159, 0x3d922279, v140
	v_fmaak_f32 v159, v140, v159, 0x3fcc422a
	v_mul_f32_e32 v159, v140, v159
	v_fmaak_f32 v164, v141, v164, 0x3fcc422a
	v_mul_f32_e32 v159, 0xbfb8aa3b, v159
	v_mul_f32_e32 v164, v141, v164
	v_exp_f32_e32 v159, v159
	v_mul_f32_e32 v164, 0xbfb8aa3b, v164
	v_exp_f32_e32 v165, v164
	v_mul_f32_e32 v168, 0x3d922279, v143
	v_add_f32_e32 v159, 1.0, v159
	v_rcp_f32_e32 v164, v159
	v_add_f32_e32 v159, 1.0, v165
	v_rcp_f32_e32 v165, v159
	v_mul_f32_e32 v159, 0x3d922279, v142
	v_fmaak_f32 v159, v142, v159, 0x3fcc422a
	v_mul_f32_e32 v159, v142, v159
	v_fmaak_f32 v168, v143, v168, 0x3fcc422a
	v_mul_f32_e32 v159, 0xbfb8aa3b, v159
	v_mul_f32_e32 v168, v143, v168
	v_exp_f32_e32 v159, v159
	v_mul_f32_e32 v168, 0xbfb8aa3b, v168
	v_exp_f32_e32 v169, v168
	v_mul_f32_e32 v170, 0x3d922279, v137
	v_add_f32_e32 v159, 1.0, v159
	v_rcp_f32_e32 v168, v159
	v_add_f32_e32 v159, 1.0, v169
	v_rcp_f32_e32 v169, v159
	v_mul_f32_e32 v159, 0x3d922279, v136
	v_fmaak_f32 v159, v136, v159, 0x3fcc422a
	v_mul_f32_e32 v159, v136, v159
	v_fmaak_f32 v170, v137, v170, 0x3fcc422a
	v_mul_f32_e32 v159, 0xbfb8aa3b, v159
	v_mul_f32_e32 v170, v137, v170
	v_exp_f32_e32 v159, v159
	v_mul_f32_e32 v170, 0xbfb8aa3b, v170
	v_exp_f32_e32 v170, v170
	v_pk_mul_f32 v[174:175], v[142:143], v[168:169]
	v_add_f32_e32 v159, 1.0, v159
	v_rcp_f32_e32 v168, v159
	v_add_f32_e32 v159, 1.0, v170
	v_rcp_f32_e32 v169, v159
	v_mul_f32_e32 v159, 0x3d922279, v138
	v_fmaak_f32 v159, v138, v159, 0x3fcc422a
	v_mul_f32_e32 v170, 0x3d922279, v139
	v_mul_f32_e32 v159, v138, v159
	v_fmaak_f32 v170, v139, v170, 0x3fcc422a
	v_mul_f32_e32 v159, 0xbfb8aa3b, v159
	v_mul_f32_e32 v170, v139, v170
	v_exp_f32_e32 v159, v159
	v_mul_f32_e32 v170, 0xbfb8aa3b, v170
	v_exp_f32_e32 v170, v170
	v_pk_mul_f32 v[176:177], v[136:137], v[168:169]
	v_add_f32_e32 v159, 1.0, v159
	v_rcp_f32_e32 v168, v159
	v_add_f32_e32 v159, 1.0, v170
	v_rcp_f32_e32 v169, v159
	v_mul_f32_e32 v159, 0x3d922279, v132
	v_fmaak_f32 v159, v132, v159, 0x3fcc422a
	v_mul_f32_e32 v170, 0x3d922279, v133
	v_mul_f32_e32 v159, v132, v159
	v_fmaak_f32 v170, v133, v170, 0x3fcc422a
	v_mul_f32_e32 v159, 0xbfb8aa3b, v159
	v_mul_f32_e32 v170, v133, v170
	v_exp_f32_e32 v159, v159
	v_mul_f32_e32 v170, 0xbfb8aa3b, v170
	v_exp_f32_e32 v170, v170
	v_pk_mul_f32 v[178:179], v[138:139], v[168:169]
	v_add_f32_e32 v159, 1.0, v159
	v_rcp_f32_e32 v168, v159
	v_add_f32_e32 v159, 1.0, v170
	v_rcp_f32_e32 v169, v159
	v_mul_f32_e32 v159, 0x3d922279, v134
	v_fmaak_f32 v159, v134, v159, 0x3fcc422a
	v_mul_f32_e32 v170, 0x3d922279, v135
	v_mul_f32_e32 v159, v134, v159
	v_fmaak_f32 v170, v135, v170, 0x3fcc422a
	v_mul_f32_e32 v159, 0xbfb8aa3b, v159
	v_mul_f32_e32 v170, v135, v170
	v_exp_f32_e32 v159, v159
	v_mul_f32_e32 v170, 0xbfb8aa3b, v170
	v_exp_f32_e32 v170, v170
	v_pk_mul_f32 v[180:181], v[132:133], v[168:169]
	v_add_f32_e32 v159, 1.0, v159
	v_rcp_f32_e32 v168, v159
	v_add_f32_e32 v159, 1.0, v170
	v_rcp_f32_e32 v169, v159
	v_pk_mul_f32 v[160:161], v[144:145], v[160:161]
	v_pk_mul_f32 v[162:163], v[146:147], v[162:163]
	v_pk_mul_f32 v[164:165], v[140:141], v[164:165]
	s_andn2_b64 vcc, exec, s[76:77]
	v_pk_mul_f32 v[182:183], v[134:135], v[168:169]
	s_cbranch_vccnz .LBB0_248
	v_pk_mul_f32 v[168:169], v[160:161], v[160:161]
	v_pk_mul_f32 v[170:171], v[162:163], v[162:163]
	v_add_f32_e32 v159, v168, v169
	v_add_f32_e32 v159, v170, v159
	v_pk_mul_f32 v[208:209], v[164:165], v[164:165]
	v_add_f32_e32 v159, v171, v159
	v_add_f32_e32 v159, v208, v159
	v_pk_mul_f32 v[210:211], v[174:175], v[174:175]
	v_add_f32_e32 v159, v209, v159
	v_add_f32_e32 v159, v210, v159
	v_pk_mul_f32 v[212:213], v[176:177], v[176:177]
	v_add_f32_e32 v159, v211, v159
	v_add_f32_e32 v159, v212, v159
	v_pk_mul_f32 v[214:215], v[178:179], v[178:179]
	v_add_f32_e32 v159, v213, v159
	v_add_f32_e32 v159, v214, v159
	v_pk_mul_f32 v[216:217], v[180:181], v[180:181]
	v_add_f32_e32 v159, v215, v159
	v_and_b32_e32 v169, 64, v196
	v_add_f32_e32 v159, v216, v159
	v_xor_b32_e32 v168, 16, v196
	v_add_u32_e32 v169, 64, v169
	v_pk_mul_f32 v[218:219], v[182:183], v[182:183]
	v_add_f32_e32 v159, v217, v159
	v_cmp_lt_i32_e32 vcc, v168, v169
	v_add_f32_e32 v159, v218, v159
	v_add_f32_e32 v159, v219, v159
	v_cndmask_b32_e32 v168, v196, v168, vcc
	v_lshlrev_b32_e32 v168, 2, v168
	ds_bpermute_b32 v168, v168, v159
	s_waitcnt lgkmcnt(0)
	v_add_f32_e32 v207, v159, v168
	v_xor_b32_e32 v159, 32, v196
	v_cmp_lt_i32_e32 vcc, v159, v169
	s_nop 1
	v_cndmask_b32_e32 v159, v196, v159, vcc
	v_lshlrev_b32_e32 v159, 2, v159
	ds_bpermute_b32 v208, v159, v207
	s_and_saveexec_b64 s[16:17], s[10:11]
	s_cbranch_execz .LBB0_247
	v_ashrrev_i32_e32 v159, 31, v158
	v_lshlrev_b64 v[168:169], 5, v[158:159]
	v_lshl_add_u64 v[168:169], s[64:65], 0, v[168:169]
	s_lshl_b32 s24, s69, 2
	v_lshl_add_u64 v[168:169], v[168:169], 0, s[24:25]
	s_lshl_b32 s24, s21, 2
	v_lshl_add_u64 v[168:169], v[168:169], 0, s[24:25]
	s_waitcnt lgkmcnt(0)
	v_add_f32_e32 v159, v207, v208
	global_store_dword v[168:169], v159, off

.LBB0_255:
	v_cndmask_b32_e64 v135, 0, 1, s[78:79]
	s_waitcnt lgkmcnt(0)
	v_pk_mul_f32 v[128:129], v[128:129], v[136:137] op_sel_hi:[1,0]
	v_pk_mul_f32 v[130:131], v[130:131], v[136:137] op_sel_hi:[1,0]
	v_pk_mul_f32 v[124:125], v[124:125], v[136:137] op_sel_hi:[1,0]
	v_pk_mul_f32 v[126:127], v[126:127], v[136:137] op_sel_hi:[1,0]
	v_pk_mul_f32 v[120:121], v[120:121], v[136:137] op_sel_hi:[1,0]
	v_pk_mul_f32 v[122:123], v[122:123], v[136:137] op_sel_hi:[1,0]
	v_pk_mul_f32 v[116:117], v[116:117], v[136:137] op_sel_hi:[1,0]
	v_pk_mul_f32 v[118:119], v[118:119], v[136:137] op_sel_hi:[1,0]
	v_cmp_ne_u32_e64 s[18:19], 1, v135
	s_andn2_b64 vcc, exec, s[78:79]
	s_mov_b64 s[78:79], -1
	s_cbranch_vccnz .LBB0_262
	s_and_b64 vcc, exec, s[14:15]
	s_cbranch_vccz .Lp1_gelu_2
	v_mov_b64_e32 v[136:137], v[128:129]
	v_mov_b64_e32 v[138:139], v[130:131]
	v_mov_b64_e32 v[140:141], v[124:125]
	v_mov_b64_e32 v[142:143], v[126:127]
	v_mov_b64_e32 v[144:145], v[120:121]
	v_mov_b64_e32 v[146:147], v[122:123]
	v_mov_b64_e32 v[158:159], v[116:117]
	v_mov_b64_e32 v[160:161], v[118:119]
	s_branch .LBB0_261
.Lp1_gelu_2:
	v_mul_f32_e32 v135, 0x3d922279, v128
	v_fmaak_f32 v135, v128, v135, 0x3fcc422a
	v_mul_f32_e32 v136, 0x3d922279, v129
	v_mul_f32_e32 v135, v128, v135
	v_fmaak_f32 v136, v129, v136, 0x3fcc422a
	v_mul_f32_e32 v135, 0xbfb8aa3b, v135
	v_mul_f32_e32 v136, v129, v136
	v_exp_f32_e32 v135, v135
	v_mul_f32_e32 v136, 0xbfb8aa3b, v136
	v_exp_f32_e32 v137, v136
	v_mul_f32_e32 v138, 0x3d922279, v131
	v_add_f32_e32 v135, 1.0, v135
	v_rcp_f32_e32 v136, v135
	v_add_f32_e32 v135, 1.0, v137
	v_rcp_f32_e32 v137, v135
	v_mul_f32_e32 v135, 0x3d922279, v130
	v_fmaak_f32 v135, v130, v135, 0x3fcc422a
	v_mul_f32_e32 v135, v130, v135
	v_fmaak_f32 v138, v131, v138, 0x3fcc422a
	v_mul_f32_e32 v135, 0xbfb8aa3b, v135
	v_mul_f32_e32 v138, v131, v138
	v_exp_f32_e32 v135, v135
	v_mul_f32_e32 v138, 0xbfb8aa3b, v138
	v_exp_f32_e32 v139, v138
	v_mul_f32_e32 v140, 0x3d922279, v125
	v_add_f32_e32 v135, 1.0, v135
	v_rcp_f32_e32 v138, v135
	v_add_f32_e32 v135, 1.0, v139
	v_rcp_f32_e32 v139, v135
	v_mul_f32_e32 v135, 0x3d922279, v124
	v_fmaak_f32 v135, v124, v135, 0x3fcc422a
	v_mul_f32_e32 v135, v124, v135
	v_fmaak_f32 v140, v125, v140, 0x3fcc422a
	v_mul_f32_e32 v135, 0xbfb8aa3b, v135
	v_mul_f32_e32 v140, v125, v140
	v_exp_f32_e32 v135, v135
	v_mul_f32_e32 v140, 0xbfb8aa3b, v140
	v_exp_f32_e32 v141, v140
	v_mul_f32_e32 v142, 0x3d922279, v127
	v_add_f32_e32 v135, 1.0, v135
	v_rcp_f32_e32 v140, v135
	v_add_f32_e32 v135, 1.0, v141
	v_rcp_f32_e32 v141, v135
	v_mul_f32_e32 v135, 0x3d922279, v126
	v_fmaak_f32 v135, v126, v135, 0x3fcc422a
	v_mul_f32_e32 v135, v126, v135
	v_fmaak_f32 v142, v127, v142, 0x3fcc422a
	v_mul_f32_e32 v135, 0xbfb8aa3b, v135
	v_mul_f32_e32 v142, v127, v142
	v_exp_f32_e32 v135, v135
	v_mul_f32_e32 v142, 0xbfb8aa3b, v142
	v_exp_f32_e32 v143, v142
	v_mul_f32_e32 v144, 0x3d922279, v121
	v_add_f32_e32 v135, 1.0, v135
	v_rcp_f32_e32 v142, v135
	v_add_f32_e32 v135, 1.0, v143
	v_rcp_f32_e32 v143, v135
	v_mul_f32_e32 v135, 0x3d922279, v120
	v_fmaak_f32 v135, v120, v135, 0x3fcc422a
	v_mul_f32_e32 v135, v120, v135
	v_fmaak_f32 v144, v121, v144, 0x3fcc422a
	v_mul_f32_e32 v135, 0xbfb8aa3b, v135
	v_mul_f32_e32 v144, v121, v144
	v_exp_f32_e32 v135, v135
	v_mul_f32_e32 v144, 0xbfb8aa3b, v144
	v_exp_f32_e32 v145, v144
	v_mul_f32_e32 v146, 0x3d922279, v123
	v_add_f32_e32 v135, 1.0, v135
	v_rcp_f32_e32 v144, v135
	v_add_f32_e32 v135, 1.0, v145
	v_rcp_f32_e32 v145, v135
	v_mul_f32_e32 v135, 0x3d922279, v122
	v_fmaak_f32 v135, v122, v135, 0x3fcc422a
	v_mul_f32_e32 v135, v122, v135
	v_fmaak_f32 v146, v123, v146, 0x3fcc422a
	v_mul_f32_e32 v135, 0xbfb8aa3b, v135
	v_mul_f32_e32 v146, v123, v146
	v_exp_f32_e32 v135, v135
	v_mul_f32_e32 v146, 0xbfb8aa3b, v146
	v_exp_f32_e32 v147, v146
	v_mul_f32_e32 v158, 0x3d922279, v117
	v_add_f32_e32 v135, 1.0, v135
	v_rcp_f32_e32 v146, v135
	v_add_f32_e32 v135, 1.0, v147
	v_rcp_f32_e32 v147, v135
	v_mul_f32_e32 v135, 0x3d922279, v116
	v_fmaak_f32 v135, v116, v135, 0x3fcc422a
	v_mul_f32_e32 v135, v116, v135
	v_fmaak_f32 v158, v117, v158, 0x3fcc422a
	v_mul_f32_e32 v135, 0xbfb8aa3b, v135
	v_mul_f32_e32 v158, v117, v158
	v_exp_f32_e32 v135, v135
	v_mul_f32_e32 v158, 0xbfb8aa3b, v158
	v_exp_f32_e32 v159, v158
	v_mul_f32_e32 v160, 0x3d922279, v119
	v_add_f32_e32 v135, 1.0, v135
	v_rcp_f32_e32 v158, v135
	v_add_f32_e32 v135, 1.0, v159
	v_rcp_f32_e32 v159, v135
	v_mul_f32_e32 v135, 0x3d922279, v118
	v_fmaak_f32 v135, v118, v135, 0x3fcc422a
	v_mul_f32_e32 v135, v118, v135
	v_fmaak_f32 v160, v119, v160, 0x3fcc422a
	v_mul_f32_e32 v135, 0xbfb8aa3b, v135
	v_mul_f32_e32 v160, v119, v160
	v_exp_f32_e32 v135, v135
	v_mul_f32_e32 v160, 0xbfb8aa3b, v160
	v_exp_f32_e32 v161, v160
	v_pk_mul_f32 v[136:137], v[128:129], v[136:137]
	v_add_f32_e32 v135, 1.0, v135
	v_rcp_f32_e32 v160, v135
	v_add_f32_e32 v135, 1.0, v161
	v_rcp_f32_e32 v161, v135
	v_pk_mul_f32 v[138:139], v[130:131], v[138:139]
	v_pk_mul_f32 v[140:141], v[124:125], v[140:141]
	v_pk_mul_f32 v[142:143], v[126:127], v[142:143]
	v_pk_mul_f32 v[144:145], v[120:121], v[144:145]
	v_pk_mul_f32 v[146:147], v[122:123], v[146:147]
	v_pk_mul_f32 v[158:159], v[116:117], v[158:159]
	s_andn2_b64 vcc, exec, s[76:77]
	v_pk_mul_f32 v[160:161], v[118:119], v[160:161]
	s_cbranch_vccnz .LBB0_261
	v_pk_mul_f32 v[162:163], v[136:137], v[136:137]
	v_pk_mul_f32 v[164:165], v[138:139], v[138:139]
	v_add_f32_e32 v135, v162, v163
	v_add_f32_e32 v135, v164, v135
	v_pk_mul_f32 v[168:169], v[140:141], v[140:141]
	v_add_f32_e32 v135, v165, v135
	v_add_f32_e32 v135, v168, v135
	v_pk_mul_f32 v[170:171], v[142:143], v[142:143]
	v_add_f32_e32 v135, v169, v135
	v_add_f32_e32 v135, v170, v135
	v_pk_mul_f32 v[174:175], v[144:145], v[144:145]
	v_add_f32_e32 v135, v171, v135
	v_add_f32_e32 v135, v174, v135
	v_pk_mul_f32 v[176:177], v[146:147], v[146:147]
	v_add_f32_e32 v135, v175, v135
	v_add_f32_e32 v135, v176, v135
	v_mbcnt_hi_u32_b32 v163, -1, v1
	v_pk_mul_f32 v[178:179], v[158:159], v[158:159]
	v_add_f32_e32 v135, v177, v135
	v_and_b32_e32 v164, 64, v163
	v_add_f32_e32 v135, v178, v135
	v_xor_b32_e32 v162, 16, v163
	v_add_u32_e32 v164, 64, v164
	v_pk_mul_f32 v[180:181], v[160:161], v[160:161]
	v_add_f32_e32 v135, v179, v135
	v_cmp_lt_i32_e32 vcc, v162, v164
	v_add_f32_e32 v135, v180, v135
	v_add_f32_e32 v135, v181, v135
	v_cndmask_b32_e32 v162, v163, v162, vcc
	v_lshlrev_b32_e32 v162, 2, v162
	ds_bpermute_b32 v162, v162, v135
	s_waitcnt lgkmcnt(0)
	v_add_f32_e32 v162, v135, v162
	v_xor_b32_e32 v135, 32, v163
	v_cmp_lt_i32_e32 vcc, v135, v164
	s_nop 1
	v_cndmask_b32_e32 v135, v163, v135, vcc
	v_lshlrev_b32_e32 v135, 2, v135
	ds_bpermute_b32 v163, v135, v162
	s_and_saveexec_b64 s[78:79], s[10:11]
	s_cbranch_execz .LBB0_260
	v_ashrrev_i32_e32 v135, 31, v134
	v_lshlrev_b64 v[164:165], 5, v[134:135]
	v_lshl_add_u64 v[164:165], s[64:65], 0, v[164:165]
	s_lshl_b32 s24, s69, 2
	v_lshl_add_u64 v[164:165], v[164:165], 0, s[24:25]
	s_lshl_b32 s24, s21, 2
	v_lshl_add_u64 v[164:165], v[164:165], 0, s[24:25]
	s_waitcnt lgkmcnt(0)
	v_add_f32_e32 v135, v162, v163
	global_store_dword v[164:165], v135, off

.LBB0_268:
	s_waitcnt lgkmcnt(0)
	v_pk_mul_f32 v[112:113], v[112:113], v[118:119] op_sel_hi:[1,0]
	v_pk_mul_f32 v[114:115], v[114:115], v[118:119] op_sel_hi:[1,0]
	v_pk_mul_f32 v[108:109], v[108:109], v[118:119] op_sel_hi:[1,0]
	v_pk_mul_f32 v[110:111], v[110:111], v[118:119] op_sel_hi:[1,0]
	v_pk_mul_f32 v[104:105], v[104:105], v[118:119] op_sel_hi:[1,0]
	v_pk_mul_f32 v[106:107], v[106:107], v[118:119] op_sel_hi:[1,0]
	v_pk_mul_f32 v[100:101], v[100:101], v[118:119] op_sel_hi:[1,0]
	v_pk_mul_f32 v[102:103], v[102:103], v[118:119] op_sel_hi:[1,0]
	s_and_b64 vcc, exec, s[18:19]
	s_mov_b64 s[78:79], -1
	s_cbranch_vccnz .LBB0_275
	s_and_b64 vcc, exec, s[14:15]
	s_cbranch_vccz .Lp1_gelu_3
	v_mov_b64_e32 v[118:119], v[112:113]
	v_mov_b64_e32 v[120:121], v[114:115]
	v_mov_b64_e32 v[122:123], v[108:109]
	v_mov_b64_e32 v[124:125], v[110:111]
	v_mov_b64_e32 v[126:127], v[104:105]
	v_mov_b64_e32 v[128:129], v[106:107]
	v_mov_b64_e32 v[130:131], v[100:101]
	v_mov_b64_e32 v[134:135], v[102:103]
	s_branch .LBB0_274
.Lp1_gelu_3:
	v_mul_f32_e32 v117, 0x3d922279, v112
	v_fmaak_f32 v117, v112, v117, 0x3fcc422a
	v_mul_f32_e32 v118, 0x3d922279, v113
	v_mul_f32_e32 v117, v112, v117
	v_fmaak_f32 v118, v113, v118, 0x3fcc422a
	v_mul_f32_e32 v117, 0xbfb8aa3b, v117
	v_mul_f32_e32 v118, v113, v118
	v_exp_f32_e32 v117, v117
	v_mul_f32_e32 v118, 0xbfb8aa3b, v118
	v_exp_f32_e32 v119, v118
	v_mul_f32_e32 v120, 0x3d922279, v115
	v_add_f32_e32 v117, 1.0, v117
	v_rcp_f32_e32 v118, v117
	v_add_f32_e32 v117, 1.0, v119
	v_rcp_f32_e32 v119, v117
	v_mul_f32_e32 v117, 0x3d922279, v114
	v_fmaak_f32 v117, v114, v117, 0x3fcc422a
	v_mul_f32_e32 v117, v114, v117
	v_fmaak_f32 v120, v115, v120, 0x3fcc422a
	v_mul_f32_e32 v117, 0xbfb8aa3b, v117
	v_mul_f32_e32 v120, v115, v120
	v_exp_f32_e32 v117, v117
	v_mul_f32_e32 v120, 0xbfb8aa3b, v120
	v_exp_f32_e32 v121, v120
	v_mul_f32_e32 v122, 0x3d922279, v109
	v_add_f32_e32 v117, 1.0, v117
	v_rcp_f32_e32 v120, v117
	v_add_f32_e32 v117, 1.0, v121
	v_rcp_f32_e32 v121, v117
	v_mul_f32_e32 v117, 0x3d922279, v108
	v_fmaak_f32 v117, v108, v117, 0x3fcc422a
	v_mul_f32_e32 v117, v108, v117
	v_fmaak_f32 v122, v109, v122, 0x3fcc422a
	v_mul_f32_e32 v117, 0xbfb8aa3b, v117
	v_mul_f32_e32 v122, v109, v122
	v_exp_f32_e32 v117, v117
	v_mul_f32_e32 v122, 0xbfb8aa3b, v122
	v_exp_f32_e32 v123, v122
	v_mul_f32_e32 v124, 0x3d922279, v111
	v_add_f32_e32 v117, 1.0, v117
	v_rcp_f32_e32 v122, v117
	v_add_f32_e32 v117, 1.0, v123
	v_rcp_f32_e32 v123, v117
	v_mul_f32_e32 v117, 0x3d922279, v110
	v_fmaak_f32 v117, v110, v117, 0x3fcc422a
	v_mul_f32_e32 v117, v110, v117
	v_fmaak_f32 v124, v111, v124, 0x3fcc422a
	v_mul_f32_e32 v117, 0xbfb8aa3b, v117
	v_mul_f32_e32 v124, v111, v124
	v_exp_f32_e32 v117, v117
	v_mul_f32_e32 v124, 0xbfb8aa3b, v124
	v_exp_f32_e32 v125, v124
	v_mul_f32_e32 v126, 0x3d922279, v105
	v_add_f32_e32 v117, 1.0, v117
	v_rcp_f32_e32 v124, v117
	v_add_f32_e32 v117, 1.0, v125
	v_rcp_f32_e32 v125, v117
	v_mul_f32_e32 v117, 0x3d922279, v104
	v_fmaak_f32 v117, v104, v117, 0x3fcc422a
	v_mul_f32_e32 v117, v104, v117
	v_fmaak_f32 v126, v105, v126, 0x3fcc422a
	v_mul_f32_e32 v117, 0xbfb8aa3b, v117
	v_mul_f32_e32 v126, v105, v126
	v_exp_f32_e32 v117, v117
	v_mul_f32_e32 v126, 0xbfb8aa3b, v126
	v_exp_f32_e32 v127, v126
	v_mul_f32_e32 v128, 0x3d922279, v107
	v_add_f32_e32 v117, 1.0, v117
	v_rcp_f32_e32 v126, v117
	v_add_f32_e32 v117, 1.0, v127
	v_rcp_f32_e32 v127, v117
	v_mul_f32_e32 v117, 0x3d922279, v106
	v_fmaak_f32 v117, v106, v117, 0x3fcc422a
	v_mul_f32_e32 v117, v106, v117
	v_fmaak_f32 v128, v107, v128, 0x3fcc422a
	v_mul_f32_e32 v117, 0xbfb8aa3b, v117
	v_mul_f32_e32 v128, v107, v128
	v_exp_f32_e32 v117, v117
	v_mul_f32_e32 v128, 0xbfb8aa3b, v128
	v_exp_f32_e32 v129, v128
	v_mul_f32_e32 v130, 0x3d922279, v101
	v_add_f32_e32 v117, 1.0, v117
	v_rcp_f32_e32 v128, v117
	v_add_f32_e32 v117, 1.0, v129
	v_rcp_f32_e32 v129, v117
	v_mul_f32_e32 v117, 0x3d922279, v100
	v_fmaak_f32 v117, v100, v117, 0x3fcc422a
	v_mul_f32_e32 v117, v100, v117
	v_fmaak_f32 v130, v101, v130, 0x3fcc422a
	v_mul_f32_e32 v117, 0xbfb8aa3b, v117
	v_mul_f32_e32 v130, v101, v130
	v_exp_f32_e32 v117, v117
	v_mul_f32_e32 v130, 0xbfb8aa3b, v130
	v_exp_f32_e32 v131, v130
	v_mul_f32_e32 v134, 0x3d922279, v103
	v_add_f32_e32 v117, 1.0, v117
	v_rcp_f32_e32 v130, v117
	v_add_f32_e32 v117, 1.0, v131
	v_rcp_f32_e32 v131, v117
	v_mul_f32_e32 v117, 0x3d922279, v102
	v_fmaak_f32 v117, v102, v117, 0x3fcc422a
	v_mul_f32_e32 v117, v102, v117
	v_fmaak_f32 v134, v103, v134, 0x3fcc422a
	v_mul_f32_e32 v117, 0xbfb8aa3b, v117
	v_mul_f32_e32 v134, v103, v134
	v_exp_f32_e32 v117, v117
	v_mul_f32_e32 v134, 0xbfb8aa3b, v134
	v_exp_f32_e32 v135, v134
	v_pk_mul_f32 v[118:119], v[112:113], v[118:119]
	v_add_f32_e32 v117, 1.0, v117
	v_rcp_f32_e32 v134, v117
	v_add_f32_e32 v117, 1.0, v135
	v_rcp_f32_e32 v135, v117
	v_pk_mul_f32 v[120:121], v[114:115], v[120:121]
	v_pk_mul_f32 v[122:123], v[108:109], v[122:123]
	v_pk_mul_f32 v[124:125], v[110:111], v[124:125]
	v_pk_mul_f32 v[126:127], v[104:105], v[126:127]
	v_pk_mul_f32 v[128:129], v[106:107], v[128:129]
	v_pk_mul_f32 v[130:131], v[100:101], v[130:131]
	s_andn2_b64 vcc, exec, s[76:77]
	v_pk_mul_f32 v[134:135], v[102:103], v[134:135]
	s_cbranch_vccnz .LBB0_274
	v_pk_mul_f32 v[136:137], v[118:119], v[118:119]
	v_pk_mul_f32 v[138:139], v[120:121], v[120:121]
	v_add_f32_e32 v117, v136, v137
	v_add_f32_e32 v117, v138, v117
	v_pk_mul_f32 v[140:141], v[122:123], v[122:123]
	v_add_f32_e32 v117, v139, v117
	v_add_f32_e32 v117, v140, v117
	v_pk_mul_f32 v[142:143], v[124:125], v[124:125]
	v_add_f32_e32 v117, v141, v117
	v_add_f32_e32 v117, v142, v117
	v_pk_mul_f32 v[144:145], v[126:127], v[126:127]
	v_add_f32_e32 v117, v143, v117
	v_add_f32_e32 v117, v144, v117
	v_pk_mul_f32 v[146:147], v[128:129], v[128:129]
	v_add_f32_e32 v117, v145, v117
	v_add_f32_e32 v117, v146, v117
	v_mbcnt_hi_u32_b32 v137, -1, v1
	v_pk_mul_f32 v[158:159], v[130:131], v[130:131]
	v_add_f32_e32 v117, v147, v117
	v_and_b32_e32 v138, 64, v137
	v_add_f32_e32 v117, v158, v117
	v_xor_b32_e32 v136, 16, v137
	v_add_u32_e32 v138, 64, v138
	v_pk_mul_f32 v[160:161], v[134:135], v[134:135]
	v_add_f32_e32 v117, v159, v117
	v_cmp_lt_i32_e32 vcc, v136, v138
	v_add_f32_e32 v117, v160, v117
	v_add_f32_e32 v117, v161, v117
	v_cndmask_b32_e32 v136, v137, v136, vcc
	v_lshlrev_b32_e32 v136, 2, v136
	ds_bpermute_b32 v136, v136, v117
	s_waitcnt lgkmcnt(0)
	v_add_f32_e32 v136, v117, v136
	v_xor_b32_e32 v117, 32, v137
	v_cmp_lt_i32_e32 vcc, v117, v138
	s_nop 1
	v_cndmask_b32_e32 v117, v137, v117, vcc
	v_lshlrev_b32_e32 v117, 2, v117
	ds_bpermute_b32 v137, v117, v136
	s_and_saveexec_b64 s[78:79], s[10:11]
	s_cbranch_execz .LBB0_273
	v_ashrrev_i32_e32 v117, 31, v116
	v_lshlrev_b64 v[138:139], 5, v[116:117]
	v_lshl_add_u64 v[138:139], s[64:65], 0, v[138:139]
	s_lshl_b32 s24, s69, 2
	v_lshl_add_u64 v[138:139], v[138:139], 0, s[24:25]
	s_lshl_b32 s24, s21, 2
	v_lshl_add_u64 v[138:139], v[138:139], 0, s[24:25]
	s_waitcnt lgkmcnt(0)
	v_add_f32_e32 v117, v136, v137
	global_store_dword v[138:139], v117, off

.LBB0_281:
	s_waitcnt lgkmcnt(0)
	v_pk_mul_f32 v[96:97], v[96:97], v[102:103] op_sel_hi:[1,0]
	v_pk_mul_f32 v[98:99], v[98:99], v[102:103] op_sel_hi:[1,0]
	v_pk_mul_f32 v[92:93], v[92:93], v[102:103] op_sel_hi:[1,0]
	v_pk_mul_f32 v[94:95], v[94:95], v[102:103] op_sel_hi:[1,0]
	v_pk_mul_f32 v[88:89], v[88:89], v[102:103] op_sel_hi:[1,0]
	v_pk_mul_f32 v[90:91], v[90:91], v[102:103] op_sel_hi:[1,0]
	v_pk_mul_f32 v[84:85], v[84:85], v[102:103] op_sel_hi:[1,0]
	v_pk_mul_f32 v[86:87], v[86:87], v[102:103] op_sel_hi:[1,0]
	s_and_b64 vcc, exec, s[18:19]
	s_mov_b64 s[78:79], -1
	s_cbranch_vccnz .LBB0_288
	s_and_b64 vcc, exec, s[14:15]
	s_cbranch_vccz .Lp1_gelu_4
	v_mov_b64_e32 v[102:103], v[96:97]
	v_mov_b64_e32 v[104:105], v[98:99]
	v_mov_b64_e32 v[106:107], v[92:93]
	v_mov_b64_e32 v[108:109], v[94:95]
	v_mov_b64_e32 v[110:111], v[88:89]
	v_mov_b64_e32 v[112:113], v[90:91]
	v_mov_b64_e32 v[114:115], v[84:85]
	v_mov_b64_e32 v[116:117], v[86:87]
	s_branch .LBB0_287
.Lp1_gelu_4:
	v_mul_f32_e32 v101, 0x3d922279, v96
	v_fmaak_f32 v101, v96, v101, 0x3fcc422a
	v_mul_f32_e32 v102, 0x3d922279, v97
	v_mul_f32_e32 v101, v96, v101
	v_fmaak_f32 v102, v97, v102, 0x3fcc422a
	v_mul_f32_e32 v101, 0xbfb8aa3b, v101
	v_mul_f32_e32 v102, v97, v102
	v_exp_f32_e32 v101, v101
	v_mul_f32_e32 v102, 0xbfb8aa3b, v102
	v_exp_f32_e32 v103, v102
	v_mul_f32_e32 v104, 0x3d922279, v99
	v_add_f32_e32 v101, 1.0, v101
	v_rcp_f32_e32 v102, v101
	v_add_f32_e32 v101, 1.0, v103
	v_rcp_f32_e32 v103, v101
	v_mul_f32_e32 v101, 0x3d922279, v98
	v_fmaak_f32 v101, v98, v101, 0x3fcc422a
	v_mul_f32_e32 v101, v98, v101
	v_fmaak_f32 v104, v99, v104, 0x3fcc422a
	v_mul_f32_e32 v101, 0xbfb8aa3b, v101
	v_mul_f32_e32 v104, v99, v104
	v_exp_f32_e32 v101, v101
	v_mul_f32_e32 v104, 0xbfb8aa3b, v104
	v_exp_f32_e32 v105, v104
	v_mul_f32_e32 v106, 0x3d922279, v93
	v_add_f32_e32 v101, 1.0, v101
	v_rcp_f32_e32 v104, v101
	v_add_f32_e32 v101, 1.0, v105
	v_rcp_f32_e32 v105, v101
	v_mul_f32_e32 v101, 0x3d922279, v92
	v_fmaak_f32 v101, v92, v101, 0x3fcc422a
	v_mul_f32_e32 v101, v92, v101
	v_fmaak_f32 v106, v93, v106, 0x3fcc422a
	v_mul_f32_e32 v101, 0xbfb8aa3b, v101
	v_mul_f32_e32 v106, v93, v106
	v_exp_f32_e32 v101, v101
	v_mul_f32_e32 v106, 0xbfb8aa3b, v106
	v_exp_f32_e32 v107, v106
	v_mul_f32_e32 v108, 0x3d922279, v95
	v_add_f32_e32 v101, 1.0, v101
	v_rcp_f32_e32 v106, v101
	v_add_f32_e32 v101, 1.0, v107
	v_rcp_f32_e32 v107, v101
	v_mul_f32_e32 v101, 0x3d922279, v94
	v_fmaak_f32 v101, v94, v101, 0x3fcc422a
	v_mul_f32_e32 v101, v94, v101
	v_fmaak_f32 v108, v95, v108, 0x3fcc422a
	v_mul_f32_e32 v101, 0xbfb8aa3b, v101
	v_mul_f32_e32 v108, v95, v108
	v_exp_f32_e32 v101, v101
	v_mul_f32_e32 v108, 0xbfb8aa3b, v108
	v_exp_f32_e32 v109, v108
	v_mul_f32_e32 v110, 0x3d922279, v89
	v_add_f32_e32 v101, 1.0, v101
	v_rcp_f32_e32 v108, v101
	v_add_f32_e32 v101, 1.0, v109
	v_rcp_f32_e32 v109, v101
	v_mul_f32_e32 v101, 0x3d922279, v88
	v_fmaak_f32 v101, v88, v101, 0x3fcc422a
	v_mul_f32_e32 v101, v88, v101
	v_fmaak_f32 v110, v89, v110, 0x3fcc422a
	v_mul_f32_e32 v101, 0xbfb8aa3b, v101
	v_mul_f32_e32 v110, v89, v110
	v_exp_f32_e32 v101, v101
	v_mul_f32_e32 v110, 0xbfb8aa3b, v110
	v_exp_f32_e32 v111, v110
	v_mul_f32_e32 v112, 0x3d922279, v91
	v_add_f32_e32 v101, 1.0, v101
	v_rcp_f32_e32 v110, v101
	v_add_f32_e32 v101, 1.0, v111
	v_rcp_f32_e32 v111, v101
	v_mul_f32_e32 v101, 0x3d922279, v90
	v_fmaak_f32 v101, v90, v101, 0x3fcc422a
	v_mul_f32_e32 v101, v90, v101
	v_fmaak_f32 v112, v91, v112, 0x3fcc422a
	v_mul_f32_e32 v101, 0xbfb8aa3b, v101
	v_mul_f32_e32 v112, v91, v112
	v_exp_f32_e32 v101, v101
	v_mul_f32_e32 v112, 0xbfb8aa3b, v112
	v_exp_f32_e32 v113, v112
	v_mul_f32_e32 v114, 0x3d922279, v85
	v_add_f32_e32 v101, 1.0, v101
	v_rcp_f32_e32 v112, v101
	v_add_f32_e32 v101, 1.0, v113
	v_rcp_f32_e32 v113, v101
	v_mul_f32_e32 v101, 0x3d922279, v84
	v_fmaak_f32 v101, v84, v101, 0x3fcc422a
	v_mul_f32_e32 v101, v84, v101
	v_fmaak_f32 v114, v85, v114, 0x3fcc422a
	v_mul_f32_e32 v101, 0xbfb8aa3b, v101
	v_mul_f32_e32 v114, v85, v114
	v_exp_f32_e32 v101, v101
	v_mul_f32_e32 v114, 0xbfb8aa3b, v114
	v_exp_f32_e32 v115, v114
	v_mul_f32_e32 v116, 0x3d922279, v87
	v_add_f32_e32 v101, 1.0, v101
	v_rcp_f32_e32 v114, v101
	v_add_f32_e32 v101, 1.0, v115
	v_rcp_f32_e32 v115, v101
	v_mul_f32_e32 v101, 0x3d922279, v86
	v_fmaak_f32 v101, v86, v101, 0x3fcc422a
	v_mul_f32_e32 v101, v86, v101
	v_fmaak_f32 v116, v87, v116, 0x3fcc422a
	v_mul_f32_e32 v101, 0xbfb8aa3b, v101
	v_mul_f32_e32 v116, v87, v116
	v_exp_f32_e32 v101, v101
	v_mul_f32_e32 v116, 0xbfb8aa3b, v116
	v_exp_f32_e32 v117, v116
	v_pk_mul_f32 v[102:103], v[96:97], v[102:103]
	v_add_f32_e32 v101, 1.0, v101
	v_rcp_f32_e32 v116, v101
	v_add_f32_e32 v101, 1.0, v117
	v_rcp_f32_e32 v117, v101
	v_pk_mul_f32 v[104:105], v[98:99], v[104:105]
	v_pk_mul_f32 v[106:107], v[92:93], v[106:107]
	v_pk_mul_f32 v[108:109], v[94:95], v[108:109]
	v_pk_mul_f32 v[110:111], v[88:89], v[110:111]
	v_pk_mul_f32 v[112:113], v[90:91], v[112:113]
	v_pk_mul_f32 v[114:115], v[84:85], v[114:115]
	s_andn2_b64 vcc, exec, s[76:77]
	v_pk_mul_f32 v[116:117], v[86:87], v[116:117]
	s_cbranch_vccnz .LBB0_287
	v_pk_mul_f32 v[118:119], v[102:103], v[102:103]
	v_pk_mul_f32 v[120:121], v[104:105], v[104:105]
	v_add_f32_e32 v101, v118, v119
	v_add_f32_e32 v101, v120, v101
	v_pk_mul_f32 v[122:123], v[106:107], v[106:107]
	v_add_f32_e32 v101, v121, v101
	v_add_f32_e32 v101, v122, v101
	v_pk_mul_f32 v[124:125], v[108:109], v[108:109]
	v_add_f32_e32 v101, v123, v101
	v_add_f32_e32 v101, v124, v101
	v_pk_mul_f32 v[126:127], v[110:111], v[110:111]
	v_add_f32_e32 v101, v125, v101
	v_add_f32_e32 v101, v126, v101
	v_pk_mul_f32 v[128:129], v[112:113], v[112:113]
	v_add_f32_e32 v101, v127, v101
	v_add_f32_e32 v101, v128, v101
	v_mbcnt_hi_u32_b32 v119, -1, v1
	v_pk_mul_f32 v[130:131], v[114:115], v[114:115]
	v_add_f32_e32 v101, v129, v101
	v_and_b32_e32 v120, 64, v119
	v_add_f32_e32 v101, v130, v101
	v_xor_b32_e32 v118, 16, v119
	v_add_u32_e32 v120, 64, v120
	v_pk_mul_f32 v[134:135], v[116:117], v[116:117]
	v_add_f32_e32 v101, v131, v101
	v_cmp_lt_i32_e32 vcc, v118, v120
	v_add_f32_e32 v101, v134, v101
	v_add_f32_e32 v101, v135, v101
	v_cndmask_b32_e32 v118, v119, v118, vcc
	v_lshlrev_b32_e32 v118, 2, v118
	ds_bpermute_b32 v118, v118, v101
	s_waitcnt lgkmcnt(0)
	v_add_f32_e32 v118, v101, v118
	v_xor_b32_e32 v101, 32, v119
	v_cmp_lt_i32_e32 vcc, v101, v120
	s_nop 1
	v_cndmask_b32_e32 v101, v119, v101, vcc
	v_lshlrev_b32_e32 v101, 2, v101
	ds_bpermute_b32 v119, v101, v118
	s_and_saveexec_b64 s[78:79], s[10:11]
	s_cbranch_execz .LBB0_286
	v_ashrrev_i32_e32 v101, 31, v100
	v_lshlrev_b64 v[120:121], 5, v[100:101]
	v_lshl_add_u64 v[120:121], s[64:65], 0, v[120:121]
	s_lshl_b32 s24, s69, 2
	v_lshl_add_u64 v[120:121], v[120:121], 0, s[24:25]
	s_lshl_b32 s24, s21, 2
	v_lshl_add_u64 v[120:121], v[120:121], 0, s[24:25]
	s_waitcnt lgkmcnt(0)
	v_add_f32_e32 v101, v118, v119
	global_store_dword v[120:121], v101, off

.LBB0_294:
	s_waitcnt lgkmcnt(0)
	v_pk_mul_f32 v[80:81], v[80:81], v[86:87] op_sel_hi:[1,0]
	v_pk_mul_f32 v[82:83], v[82:83], v[86:87] op_sel_hi:[1,0]
	v_pk_mul_f32 v[76:77], v[76:77], v[86:87] op_sel_hi:[1,0]
	v_pk_mul_f32 v[78:79], v[78:79], v[86:87] op_sel_hi:[1,0]
	v_pk_mul_f32 v[72:73], v[72:73], v[86:87] op_sel_hi:[1,0]
	v_pk_mul_f32 v[74:75], v[74:75], v[86:87] op_sel_hi:[1,0]
	v_pk_mul_f32 v[68:69], v[68:69], v[86:87] op_sel_hi:[1,0]
	v_pk_mul_f32 v[70:71], v[70:71], v[86:87] op_sel_hi:[1,0]
	s_and_b64 vcc, exec, s[18:19]
	s_mov_b64 s[78:79], -1
	s_cbranch_vccnz .LBB0_301
	s_and_b64 vcc, exec, s[14:15]
	s_cbranch_vccz .Lp1_gelu_5
	v_mov_b64_e32 v[86:87], v[80:81]
	v_mov_b64_e32 v[88:89], v[82:83]
	v_mov_b64_e32 v[90:91], v[76:77]
	v_mov_b64_e32 v[92:93], v[78:79]
	v_mov_b64_e32 v[94:95], v[72:73]
	v_mov_b64_e32 v[96:97], v[74:75]
	v_mov_b64_e32 v[98:99], v[68:69]
	v_mov_b64_e32 v[100:101], v[70:71]
	s_branch .LBB0_300
.Lp1_gelu_5:
	v_mul_f32_e32 v85, 0x3d922279, v80
	v_fmaak_f32 v85, v80, v85, 0x3fcc422a
	v_mul_f32_e32 v86, 0x3d922279, v81
	v_mul_f32_e32 v85, v80, v85
	v_fmaak_f32 v86, v81, v86, 0x3fcc422a
	v_mul_f32_e32 v85, 0xbfb8aa3b, v85
	v_mul_f32_e32 v86, v81, v86
	v_exp_f32_e32 v85, v85
	v_mul_f32_e32 v86, 0xbfb8aa3b, v86
	v_exp_f32_e32 v87, v86
	v_mul_f32_e32 v88, 0x3d922279, v83
	v_add_f32_e32 v85, 1.0, v85
	v_rcp_f32_e32 v86, v85
	v_add_f32_e32 v85, 1.0, v87
	v_rcp_f32_e32 v87, v85
	v_mul_f32_e32 v85, 0x3d922279, v82
	v_fmaak_f32 v85, v82, v85, 0x3fcc422a
	v_mul_f32_e32 v85, v82, v85
	v_fmaak_f32 v88, v83, v88, 0x3fcc422a
	v_mul_f32_e32 v85, 0xbfb8aa3b, v85
	v_mul_f32_e32 v88, v83, v88
	v_exp_f32_e32 v85, v85
	v_mul_f32_e32 v88, 0xbfb8aa3b, v88
	v_exp_f32_e32 v89, v88
	v_mul_f32_e32 v90, 0x3d922279, v77
	v_add_f32_e32 v85, 1.0, v85
	v_rcp_f32_e32 v88, v85
	v_add_f32_e32 v85, 1.0, v89
	v_rcp_f32_e32 v89, v85
	v_mul_f32_e32 v85, 0x3d922279, v76
	v_fmaak_f32 v85, v76, v85, 0x3fcc422a
	v_mul_f32_e32 v85, v76, v85
	v_fmaak_f32 v90, v77, v90, 0x3fcc422a
	v_mul_f32_e32 v85, 0xbfb8aa3b, v85
	v_mul_f32_e32 v90, v77, v90
	v_exp_f32_e32 v85, v85
	v_mul_f32_e32 v90, 0xbfb8aa3b, v90
	v_exp_f32_e32 v91, v90
	v_mul_f32_e32 v92, 0x3d922279, v79
	v_add_f32_e32 v85, 1.0, v85
	v_rcp_f32_e32 v90, v85
	v_add_f32_e32 v85, 1.0, v91
	v_rcp_f32_e32 v91, v85
	v_mul_f32_e32 v85, 0x3d922279, v78
	v_fmaak_f32 v85, v78, v85, 0x3fcc422a
	v_mul_f32_e32 v85, v78, v85
	v_fmaak_f32 v92, v79, v92, 0x3fcc422a
	v_mul_f32_e32 v85, 0xbfb8aa3b, v85
	v_mul_f32_e32 v92, v79, v92
	v_exp_f32_e32 v85, v85
	v_mul_f32_e32 v92, 0xbfb8aa3b, v92
	v_exp_f32_e32 v93, v92
	v_mul_f32_e32 v94, 0x3d922279, v73
	v_add_f32_e32 v85, 1.0, v85
	v_rcp_f32_e32 v92, v85
	v_add_f32_e32 v85, 1.0, v93
	v_rcp_f32_e32 v93, v85
	v_mul_f32_e32 v85, 0x3d922279, v72
	v_fmaak_f32 v85, v72, v85, 0x3fcc422a
	v_mul_f32_e32 v85, v72, v85
	v_fmaak_f32 v94, v73, v94, 0x3fcc422a
	v_mul_f32_e32 v85, 0xbfb8aa3b, v85
	v_mul_f32_e32 v94, v73, v94
	v_exp_f32_e32 v85, v85
	v_mul_f32_e32 v94, 0xbfb8aa3b, v94
	v_exp_f32_e32 v95, v94
	v_mul_f32_e32 v96, 0x3d922279, v75
	v_add_f32_e32 v85, 1.0, v85
	v_rcp_f32_e32 v94, v85
	v_add_f32_e32 v85, 1.0, v95
	v_rcp_f32_e32 v95, v85
	v_mul_f32_e32 v85, 0x3d922279, v74
	v_fmaak_f32 v85, v74, v85, 0x3fcc422a
	v_mul_f32_e32 v85, v74, v85
	v_fmaak_f32 v96, v75, v96, 0x3fcc422a
	v_mul_f32_e32 v85, 0xbfb8aa3b, v85
	v_mul_f32_e32 v96, v75, v96
	v_exp_f32_e32 v85, v85
	v_mul_f32_e32 v96, 0xbfb8aa3b, v96
	v_exp_f32_e32 v97, v96
	v_mul_f32_e32 v98, 0x3d922279, v69
	v_add_f32_e32 v85, 1.0, v85
	v_rcp_f32_e32 v96, v85
	v_add_f32_e32 v85, 1.0, v97
	v_rcp_f32_e32 v97, v85
	v_mul_f32_e32 v85, 0x3d922279, v68
	v_fmaak_f32 v85, v68, v85, 0x3fcc422a
	v_mul_f32_e32 v85, v68, v85
	v_fmaak_f32 v98, v69, v98, 0x3fcc422a
	v_mul_f32_e32 v85, 0xbfb8aa3b, v85
	v_mul_f32_e32 v98, v69, v98
	v_exp_f32_e32 v85, v85
	v_mul_f32_e32 v98, 0xbfb8aa3b, v98
	v_exp_f32_e32 v99, v98
	v_mul_f32_e32 v100, 0x3d922279, v71
	v_add_f32_e32 v85, 1.0, v85
	v_rcp_f32_e32 v98, v85
	v_add_f32_e32 v85, 1.0, v99
	v_rcp_f32_e32 v99, v85
	v_mul_f32_e32 v85, 0x3d922279, v70
	v_fmaak_f32 v85, v70, v85, 0x3fcc422a
	v_mul_f32_e32 v85, v70, v85
	v_fmaak_f32 v100, v71, v100, 0x3fcc422a
	v_mul_f32_e32 v85, 0xbfb8aa3b, v85
	v_mul_f32_e32 v100, v71, v100
	v_exp_f32_e32 v85, v85
	v_mul_f32_e32 v100, 0xbfb8aa3b, v100
	v_exp_f32_e32 v101, v100
	v_pk_mul_f32 v[86:87], v[80:81], v[86:87]
	v_add_f32_e32 v85, 1.0, v85
	v_rcp_f32_e32 v100, v85
	v_add_f32_e32 v85, 1.0, v101
	v_rcp_f32_e32 v101, v85
	v_pk_mul_f32 v[88:89], v[82:83], v[88:89]
	v_pk_mul_f32 v[90:91], v[76:77], v[90:91]
	v_pk_mul_f32 v[92:93], v[78:79], v[92:93]
	v_pk_mul_f32 v[94:95], v[72:73], v[94:95]
	v_pk_mul_f32 v[96:97], v[74:75], v[96:97]
	v_pk_mul_f32 v[98:99], v[68:69], v[98:99]
	s_andn2_b64 vcc, exec, s[76:77]
	v_pk_mul_f32 v[100:101], v[70:71], v[100:101]
	s_cbranch_vccnz .LBB0_300
	v_pk_mul_f32 v[102:103], v[86:87], v[86:87]
	v_pk_mul_f32 v[104:105], v[88:89], v[88:89]
	v_add_f32_e32 v85, v102, v103
	v_add_f32_e32 v85, v104, v85
	v_pk_mul_f32 v[106:107], v[90:91], v[90:91]
	v_add_f32_e32 v85, v105, v85
	v_add_f32_e32 v85, v106, v85
	v_pk_mul_f32 v[108:109], v[92:93], v[92:93]
	v_add_f32_e32 v85, v107, v85
	v_add_f32_e32 v85, v108, v85
	v_pk_mul_f32 v[110:111], v[94:95], v[94:95]
	v_add_f32_e32 v85, v109, v85
	v_add_f32_e32 v85, v110, v85
	v_pk_mul_f32 v[112:113], v[96:97], v[96:97]
	v_add_f32_e32 v85, v111, v85
	v_add_f32_e32 v85, v112, v85
	v_mbcnt_hi_u32_b32 v103, -1, v1
	v_pk_mul_f32 v[114:115], v[98:99], v[98:99]
	v_add_f32_e32 v85, v113, v85
	v_and_b32_e32 v104, 64, v103
	v_add_f32_e32 v85, v114, v85
	v_xor_b32_e32 v102, 16, v103
	v_add_u32_e32 v104, 64, v104
	v_pk_mul_f32 v[116:117], v[100:101], v[100:101]
	v_add_f32_e32 v85, v115, v85
	v_cmp_lt_i32_e32 vcc, v102, v104
	v_add_f32_e32 v85, v116, v85
	v_add_f32_e32 v85, v117, v85
	v_cndmask_b32_e32 v102, v103, v102, vcc
	v_lshlrev_b32_e32 v102, 2, v102
	ds_bpermute_b32 v102, v102, v85
	s_waitcnt lgkmcnt(0)
	v_add_f32_e32 v102, v85, v102
	v_xor_b32_e32 v85, 32, v103
	v_cmp_lt_i32_e32 vcc, v85, v104
	s_nop 1
	v_cndmask_b32_e32 v85, v103, v85, vcc
	v_lshlrev_b32_e32 v85, 2, v85
	ds_bpermute_b32 v103, v85, v102
	s_and_saveexec_b64 s[78:79], s[10:11]
	s_cbranch_execz .LBB0_299
	v_ashrrev_i32_e32 v85, 31, v84
	v_lshlrev_b64 v[104:105], 5, v[84:85]
	v_lshl_add_u64 v[104:105], s[64:65], 0, v[104:105]
	s_lshl_b32 s24, s69, 2
	v_lshl_add_u64 v[104:105], v[104:105], 0, s[24:25]
	s_lshl_b32 s24, s21, 2
	v_lshl_add_u64 v[104:105], v[104:105], 0, s[24:25]
	s_waitcnt lgkmcnt(0)
	v_add_f32_e32 v85, v102, v103
	global_store_dword v[104:105], v85, off

.LBB0_307:
	s_waitcnt lgkmcnt(0)
	v_pk_mul_f32 v[64:65], v[64:65], v[70:71] op_sel_hi:[1,0]
	v_pk_mul_f32 v[66:67], v[66:67], v[70:71] op_sel_hi:[1,0]
	v_pk_mul_f32 v[60:61], v[60:61], v[70:71] op_sel_hi:[1,0]
	v_pk_mul_f32 v[62:63], v[62:63], v[70:71] op_sel_hi:[1,0]
	v_pk_mul_f32 v[56:57], v[56:57], v[70:71] op_sel_hi:[1,0]
	v_pk_mul_f32 v[58:59], v[58:59], v[70:71] op_sel_hi:[1,0]
	v_pk_mul_f32 v[52:53], v[52:53], v[70:71] op_sel_hi:[1,0]
	v_pk_mul_f32 v[54:55], v[54:55], v[70:71] op_sel_hi:[1,0]
	s_and_b64 vcc, exec, s[18:19]
	s_mov_b64 s[78:79], -1
	s_cbranch_vccnz .LBB0_314
	s_and_b64 vcc, exec, s[14:15]
	s_cbranch_vccz .Lp1_gelu_6
	v_mov_b64_e32 v[70:71], v[64:65]
	v_mov_b64_e32 v[72:73], v[66:67]
	v_mov_b64_e32 v[74:75], v[60:61]
	v_mov_b64_e32 v[76:77], v[62:63]
	v_mov_b64_e32 v[78:79], v[56:57]
	v_mov_b64_e32 v[80:81], v[58:59]
	v_mov_b64_e32 v[82:83], v[52:53]
	v_mov_b64_e32 v[84:85], v[54:55]
	s_branch .LBB0_313
.Lp1_gelu_6:
	v_mul_f32_e32 v69, 0x3d922279, v64
	v_fmaak_f32 v69, v64, v69, 0x3fcc422a
	v_mul_f32_e32 v70, 0x3d922279, v65
	v_mul_f32_e32 v69, v64, v69
	v_fmaak_f32 v70, v65, v70, 0x3fcc422a
	v_mul_f32_e32 v69, 0xbfb8aa3b, v69
	v_mul_f32_e32 v70, v65, v70
	v_exp_f32_e32 v69, v69
	v_mul_f32_e32 v70, 0xbfb8aa3b, v70
	v_exp_f32_e32 v71, v70
	v_mul_f32_e32 v72, 0x3d922279, v67
	v_add_f32_e32 v69, 1.0, v69
	v_rcp_f32_e32 v70, v69
	v_add_f32_e32 v69, 1.0, v71
	v_rcp_f32_e32 v71, v69
	v_mul_f32_e32 v69, 0x3d922279, v66
	v_fmaak_f32 v69, v66, v69, 0x3fcc422a
	v_mul_f32_e32 v69, v66, v69
	v_fmaak_f32 v72, v67, v72, 0x3fcc422a
	v_mul_f32_e32 v69, 0xbfb8aa3b, v69
	v_mul_f32_e32 v72, v67, v72
	v_exp_f32_e32 v69, v69
	v_mul_f32_e32 v72, 0xbfb8aa3b, v72
	v_exp_f32_e32 v73, v72
	v_mul_f32_e32 v74, 0x3d922279, v61
	v_add_f32_e32 v69, 1.0, v69
	v_rcp_f32_e32 v72, v69
	v_add_f32_e32 v69, 1.0, v73
	v_rcp_f32_e32 v73, v69
	v_mul_f32_e32 v69, 0x3d922279, v60
	v_fmaak_f32 v69, v60, v69, 0x3fcc422a
	v_mul_f32_e32 v69, v60, v69
	v_fmaak_f32 v74, v61, v74, 0x3fcc422a
	v_mul_f32_e32 v69, 0xbfb8aa3b, v69
	v_mul_f32_e32 v74, v61, v74
	v_exp_f32_e32 v69, v69
	v_mul_f32_e32 v74, 0xbfb8aa3b, v74
	v_exp_f32_e32 v75, v74
	v_mul_f32_e32 v76, 0x3d922279, v63
	v_add_f32_e32 v69, 1.0, v69
	v_rcp_f32_e32 v74, v69
	v_add_f32_e32 v69, 1.0, v75
	v_rcp_f32_e32 v75, v69
	v_mul_f32_e32 v69, 0x3d922279, v62
	v_fmaak_f32 v69, v62, v69, 0x3fcc422a
	v_mul_f32_e32 v69, v62, v69
	v_fmaak_f32 v76, v63, v76, 0x3fcc422a
	v_mul_f32_e32 v69, 0xbfb8aa3b, v69
	v_mul_f32_e32 v76, v63, v76
	v_exp_f32_e32 v69, v69
	v_mul_f32_e32 v76, 0xbfb8aa3b, v76
	v_exp_f32_e32 v77, v76
	v_mul_f32_e32 v78, 0x3d922279, v57
	v_add_f32_e32 v69, 1.0, v69
	v_rcp_f32_e32 v76, v69
	v_add_f32_e32 v69, 1.0, v77
	v_rcp_f32_e32 v77, v69
	v_mul_f32_e32 v69, 0x3d922279, v56
	v_fmaak_f32 v69, v56, v69, 0x3fcc422a
	v_mul_f32_e32 v69, v56, v69
	v_fmaak_f32 v78, v57, v78, 0x3fcc422a
	v_mul_f32_e32 v69, 0xbfb8aa3b, v69
	v_mul_f32_e32 v78, v57, v78
	v_exp_f32_e32 v69, v69
	v_mul_f32_e32 v78, 0xbfb8aa3b, v78
	v_exp_f32_e32 v79, v78
	v_mul_f32_e32 v80, 0x3d922279, v59
	v_add_f32_e32 v69, 1.0, v69
	v_rcp_f32_e32 v78, v69
	v_add_f32_e32 v69, 1.0, v79
	v_rcp_f32_e32 v79, v69
	v_mul_f32_e32 v69, 0x3d922279, v58
	v_fmaak_f32 v69, v58, v69, 0x3fcc422a
	v_mul_f32_e32 v69, v58, v69
	v_fmaak_f32 v80, v59, v80, 0x3fcc422a
	v_mul_f32_e32 v69, 0xbfb8aa3b, v69
	v_mul_f32_e32 v80, v59, v80
	v_exp_f32_e32 v69, v69
	v_mul_f32_e32 v80, 0xbfb8aa3b, v80
	v_exp_f32_e32 v81, v80
	v_mul_f32_e32 v82, 0x3d922279, v53
	v_add_f32_e32 v69, 1.0, v69
	v_rcp_f32_e32 v80, v69
	v_add_f32_e32 v69, 1.0, v81
	v_rcp_f32_e32 v81, v69
	v_mul_f32_e32 v69, 0x3d922279, v52
	v_fmaak_f32 v69, v52, v69, 0x3fcc422a
	v_mul_f32_e32 v69, v52, v69
	v_fmaak_f32 v82, v53, v82, 0x3fcc422a
	v_mul_f32_e32 v69, 0xbfb8aa3b, v69
	v_mul_f32_e32 v82, v53, v82
	v_exp_f32_e32 v69, v69
	v_mul_f32_e32 v82, 0xbfb8aa3b, v82
	v_exp_f32_e32 v83, v82
	v_mul_f32_e32 v84, 0x3d922279, v55
	v_add_f32_e32 v69, 1.0, v69
	v_rcp_f32_e32 v82, v69
	v_add_f32_e32 v69, 1.0, v83
	v_rcp_f32_e32 v83, v69
	v_mul_f32_e32 v69, 0x3d922279, v54
	v_fmaak_f32 v69, v54, v69, 0x3fcc422a
	v_mul_f32_e32 v69, v54, v69
	v_fmaak_f32 v84, v55, v84, 0x3fcc422a
	v_mul_f32_e32 v69, 0xbfb8aa3b, v69
	v_mul_f32_e32 v84, v55, v84
	v_exp_f32_e32 v69, v69
	v_mul_f32_e32 v84, 0xbfb8aa3b, v84
	v_exp_f32_e32 v85, v84
	v_pk_mul_f32 v[70:71], v[64:65], v[70:71]
	v_add_f32_e32 v69, 1.0, v69
	v_rcp_f32_e32 v84, v69
	v_add_f32_e32 v69, 1.0, v85
	v_rcp_f32_e32 v85, v69
	v_pk_mul_f32 v[72:73], v[66:67], v[72:73]
	v_pk_mul_f32 v[74:75], v[60:61], v[74:75]
	v_pk_mul_f32 v[76:77], v[62:63], v[76:77]
	v_pk_mul_f32 v[78:79], v[56:57], v[78:79]
	v_pk_mul_f32 v[80:81], v[58:59], v[80:81]
	v_pk_mul_f32 v[82:83], v[52:53], v[82:83]
	s_andn2_b64 vcc, exec, s[76:77]
	v_pk_mul_f32 v[84:85], v[54:55], v[84:85]
	s_cbranch_vccnz .LBB0_313
	v_pk_mul_f32 v[86:87], v[70:71], v[70:71]
	v_pk_mul_f32 v[88:89], v[72:73], v[72:73]
	v_add_f32_e32 v69, v86, v87
	v_add_f32_e32 v69, v88, v69
	v_pk_mul_f32 v[90:91], v[74:75], v[74:75]
	v_add_f32_e32 v69, v89, v69
	v_add_f32_e32 v69, v90, v69
	v_pk_mul_f32 v[92:93], v[76:77], v[76:77]
	v_add_f32_e32 v69, v91, v69
	v_add_f32_e32 v69, v92, v69
	v_pk_mul_f32 v[94:95], v[78:79], v[78:79]
	v_add_f32_e32 v69, v93, v69
	v_add_f32_e32 v69, v94, v69
	v_pk_mul_f32 v[96:97], v[80:81], v[80:81]
	v_add_f32_e32 v69, v95, v69
	v_add_f32_e32 v69, v96, v69
	v_mbcnt_hi_u32_b32 v87, -1, v1
	v_pk_mul_f32 v[98:99], v[82:83], v[82:83]
	v_add_f32_e32 v69, v97, v69
	v_and_b32_e32 v88, 64, v87
	v_add_f32_e32 v69, v98, v69
	v_xor_b32_e32 v86, 16, v87
	v_add_u32_e32 v88, 64, v88
	v_pk_mul_f32 v[100:101], v[84:85], v[84:85]
	v_add_f32_e32 v69, v99, v69
	v_cmp_lt_i32_e32 vcc, v86, v88
	v_add_f32_e32 v69, v100, v69
	v_add_f32_e32 v69, v101, v69
	v_cndmask_b32_e32 v86, v87, v86, vcc
	v_lshlrev_b32_e32 v86, 2, v86
	ds_bpermute_b32 v86, v86, v69
	s_waitcnt lgkmcnt(0)
	v_add_f32_e32 v86, v69, v86
	v_xor_b32_e32 v69, 32, v87
	v_cmp_lt_i32_e32 vcc, v69, v88
	s_nop 1
	v_cndmask_b32_e32 v69, v87, v69, vcc
	v_lshlrev_b32_e32 v69, 2, v69
	ds_bpermute_b32 v87, v69, v86
	s_and_saveexec_b64 s[78:79], s[10:11]
	s_cbranch_execz .LBB0_312
	v_ashrrev_i32_e32 v69, 31, v68
	v_lshlrev_b64 v[88:89], 5, v[68:69]
	v_lshl_add_u64 v[88:89], s[64:65], 0, v[88:89]
	s_lshl_b32 s24, s69, 2
	v_lshl_add_u64 v[88:89], v[88:89], 0, s[24:25]
	s_lshl_b32 s24, s21, 2
	v_lshl_add_u64 v[88:89], v[88:89], 0, s[24:25]
	s_waitcnt lgkmcnt(0)
	v_add_f32_e32 v69, v86, v87
	global_store_dword v[88:89], v69, off

.LBB0_320:
	s_waitcnt lgkmcnt(0)
	v_pk_mul_f32 v[48:49], v[48:49], v[54:55] op_sel_hi:[1,0]
	v_pk_mul_f32 v[50:51], v[50:51], v[54:55] op_sel_hi:[1,0]
	v_pk_mul_f32 v[44:45], v[44:45], v[54:55] op_sel_hi:[1,0]
	v_pk_mul_f32 v[46:47], v[46:47], v[54:55] op_sel_hi:[1,0]
	v_pk_mul_f32 v[40:41], v[40:41], v[54:55] op_sel_hi:[1,0]
	v_pk_mul_f32 v[42:43], v[42:43], v[54:55] op_sel_hi:[1,0]
	v_pk_mul_f32 v[32:33], v[32:33], v[54:55] op_sel_hi:[1,0]
	v_pk_mul_f32 v[34:35], v[34:35], v[54:55] op_sel_hi:[1,0]
	s_and_b64 vcc, exec, s[18:19]
	s_mov_b64 s[78:79], -1
	s_cbranch_vccnz .LBB0_327
	s_and_b64 vcc, exec, s[14:15]
	s_cbranch_vccz .Lp1_gelu_7
	v_mov_b64_e32 v[54:55], v[48:49]
	v_mov_b64_e32 v[56:57], v[50:51]
	v_mov_b64_e32 v[58:59], v[44:45]
	v_mov_b64_e32 v[60:61], v[46:47]
	v_mov_b64_e32 v[62:63], v[40:41]
	v_mov_b64_e32 v[64:65], v[42:43]
	v_mov_b64_e32 v[66:67], v[32:33]
	v_mov_b64_e32 v[68:69], v[34:35]
	s_branch .LBB0_326
.Lp1_gelu_7:
	v_mul_f32_e32 v53, 0x3d922279, v48
	v_fmaak_f32 v53, v48, v53, 0x3fcc422a
	v_mul_f32_e32 v54, 0x3d922279, v49
	v_mul_f32_e32 v53, v48, v53
	v_fmaak_f32 v54, v49, v54, 0x3fcc422a
	v_mul_f32_e32 v53, 0xbfb8aa3b, v53
	v_mul_f32_e32 v54, v49, v54
	v_exp_f32_e32 v53, v53
	v_mul_f32_e32 v54, 0xbfb8aa3b, v54
	v_exp_f32_e32 v55, v54
	v_mul_f32_e32 v56, 0x3d922279, v51
	v_add_f32_e32 v53, 1.0, v53
	v_rcp_f32_e32 v54, v53
	v_add_f32_e32 v53, 1.0, v55
	v_rcp_f32_e32 v55, v53
	v_mul_f32_e32 v53, 0x3d922279, v50
	v_fmaak_f32 v53, v50, v53, 0x3fcc422a
	v_mul_f32_e32 v53, v50, v53
	v_fmaak_f32 v56, v51, v56, 0x3fcc422a
	v_mul_f32_e32 v53, 0xbfb8aa3b, v53
	v_mul_f32_e32 v56, v51, v56
	v_exp_f32_e32 v53, v53
	v_mul_f32_e32 v56, 0xbfb8aa3b, v56
	v_exp_f32_e32 v57, v56
	v_mul_f32_e32 v58, 0x3d922279, v45
	v_add_f32_e32 v53, 1.0, v53
	v_rcp_f32_e32 v56, v53
	v_add_f32_e32 v53, 1.0, v57
	v_rcp_f32_e32 v57, v53
	v_mul_f32_e32 v53, 0x3d922279, v44
	v_fmaak_f32 v53, v44, v53, 0x3fcc422a
	v_mul_f32_e32 v53, v44, v53
	v_fmaak_f32 v58, v45, v58, 0x3fcc422a
	v_mul_f32_e32 v53, 0xbfb8aa3b, v53
	v_mul_f32_e32 v58, v45, v58
	v_exp_f32_e32 v53, v53
	v_mul_f32_e32 v58, 0xbfb8aa3b, v58
	v_exp_f32_e32 v59, v58
	v_mul_f32_e32 v60, 0x3d922279, v47
	v_add_f32_e32 v53, 1.0, v53
	v_rcp_f32_e32 v58, v53
	v_add_f32_e32 v53, 1.0, v59
	v_rcp_f32_e32 v59, v53
	v_mul_f32_e32 v53, 0x3d922279, v46
	v_fmaak_f32 v53, v46, v53, 0x3fcc422a
	v_mul_f32_e32 v53, v46, v53
	v_fmaak_f32 v60, v47, v60, 0x3fcc422a
	v_mul_f32_e32 v53, 0xbfb8aa3b, v53
	v_mul_f32_e32 v60, v47, v60
	v_exp_f32_e32 v53, v53
	v_mul_f32_e32 v60, 0xbfb8aa3b, v60
	v_exp_f32_e32 v61, v60
	v_mul_f32_e32 v62, 0x3d922279, v41
	v_add_f32_e32 v53, 1.0, v53
	v_rcp_f32_e32 v60, v53
	v_add_f32_e32 v53, 1.0, v61
	v_rcp_f32_e32 v61, v53
	v_mul_f32_e32 v53, 0x3d922279, v40
	v_fmaak_f32 v53, v40, v53, 0x3fcc422a
	v_mul_f32_e32 v53, v40, v53
	v_fmaak_f32 v62, v41, v62, 0x3fcc422a
	v_mul_f32_e32 v53, 0xbfb8aa3b, v53
	v_mul_f32_e32 v62, v41, v62
	v_exp_f32_e32 v53, v53
	v_mul_f32_e32 v62, 0xbfb8aa3b, v62
	v_exp_f32_e32 v63, v62
	v_mul_f32_e32 v64, 0x3d922279, v43
	v_add_f32_e32 v53, 1.0, v53
	v_rcp_f32_e32 v62, v53
	v_add_f32_e32 v53, 1.0, v63
	v_rcp_f32_e32 v63, v53
	v_mul_f32_e32 v53, 0x3d922279, v42
	v_fmaak_f32 v53, v42, v53, 0x3fcc422a
	v_mul_f32_e32 v53, v42, v53
	v_fmaak_f32 v64, v43, v64, 0x3fcc422a
	v_mul_f32_e32 v53, 0xbfb8aa3b, v53
	v_mul_f32_e32 v64, v43, v64
	v_exp_f32_e32 v53, v53
	v_mul_f32_e32 v64, 0xbfb8aa3b, v64
	v_exp_f32_e32 v65, v64
	v_mul_f32_e32 v66, 0x3d922279, v33
	v_add_f32_e32 v53, 1.0, v53
	v_rcp_f32_e32 v64, v53
	v_add_f32_e32 v53, 1.0, v65
	v_rcp_f32_e32 v65, v53
	v_mul_f32_e32 v53, 0x3d922279, v32
	v_fmaak_f32 v53, v32, v53, 0x3fcc422a
	v_mul_f32_e32 v53, v32, v53
	v_fmaak_f32 v66, v33, v66, 0x3fcc422a
	v_mul_f32_e32 v53, 0xbfb8aa3b, v53
	v_mul_f32_e32 v66, v33, v66
	v_exp_f32_e32 v53, v53
	v_mul_f32_e32 v66, 0xbfb8aa3b, v66
	v_exp_f32_e32 v67, v66
	v_mul_f32_e32 v68, 0x3d922279, v35
	v_add_f32_e32 v53, 1.0, v53
	v_rcp_f32_e32 v66, v53
	v_add_f32_e32 v53, 1.0, v67
	v_rcp_f32_e32 v67, v53
	v_mul_f32_e32 v53, 0x3d922279, v34
	v_fmaak_f32 v53, v34, v53, 0x3fcc422a
	v_mul_f32_e32 v53, v34, v53
	v_fmaak_f32 v68, v35, v68, 0x3fcc422a
	v_mul_f32_e32 v53, 0xbfb8aa3b, v53
	v_mul_f32_e32 v68, v35, v68
	v_exp_f32_e32 v53, v53
	v_mul_f32_e32 v68, 0xbfb8aa3b, v68
	v_exp_f32_e32 v69, v68
	v_pk_mul_f32 v[54:55], v[48:49], v[54:55]
	v_add_f32_e32 v53, 1.0, v53
	v_rcp_f32_e32 v68, v53
	v_add_f32_e32 v53, 1.0, v69
	v_rcp_f32_e32 v69, v53
	v_pk_mul_f32 v[56:57], v[50:51], v[56:57]
	v_pk_mul_f32 v[58:59], v[44:45], v[58:59]
	v_pk_mul_f32 v[60:61], v[46:47], v[60:61]
	v_pk_mul_f32 v[62:63], v[40:41], v[62:63]
	v_pk_mul_f32 v[64:65], v[42:43], v[64:65]
	v_pk_mul_f32 v[66:67], v[32:33], v[66:67]
	s_andn2_b64 vcc, exec, s[76:77]
	v_pk_mul_f32 v[68:69], v[34:35], v[68:69]
	s_cbranch_vccnz .LBB0_326
	v_pk_mul_f32 v[70:71], v[54:55], v[54:55]
	v_pk_mul_f32 v[72:73], v[56:57], v[56:57]
	v_add_f32_e32 v53, v70, v71
	v_add_f32_e32 v53, v72, v53
	v_pk_mul_f32 v[74:75], v[58:59], v[58:59]
	v_add_f32_e32 v53, v73, v53
	v_add_f32_e32 v53, v74, v53
	v_pk_mul_f32 v[76:77], v[60:61], v[60:61]
	v_add_f32_e32 v53, v75, v53
	v_add_f32_e32 v53, v76, v53
	v_pk_mul_f32 v[78:79], v[62:63], v[62:63]
	v_add_f32_e32 v53, v77, v53
	v_add_f32_e32 v53, v78, v53
	v_pk_mul_f32 v[80:81], v[64:65], v[64:65]
	v_add_f32_e32 v53, v79, v53
	v_add_f32_e32 v53, v80, v53
	v_mbcnt_hi_u32_b32 v71, -1, v1
	v_pk_mul_f32 v[82:83], v[66:67], v[66:67]
	v_add_f32_e32 v53, v81, v53
	v_and_b32_e32 v72, 64, v71
	v_add_f32_e32 v53, v82, v53
	v_xor_b32_e32 v70, 16, v71
	v_add_u32_e32 v72, 64, v72
	v_pk_mul_f32 v[84:85], v[68:69], v[68:69]
	v_add_f32_e32 v53, v83, v53
	v_cmp_lt_i32_e32 vcc, v70, v72
	v_add_f32_e32 v53, v84, v53
	v_add_f32_e32 v53, v85, v53
	v_cndmask_b32_e32 v70, v71, v70, vcc
	v_lshlrev_b32_e32 v70, 2, v70
	ds_bpermute_b32 v70, v70, v53
	s_waitcnt lgkmcnt(0)
	v_add_f32_e32 v70, v53, v70
	v_xor_b32_e32 v53, 32, v71
	v_cmp_lt_i32_e32 vcc, v53, v72
	s_nop 1
	v_cndmask_b32_e32 v53, v71, v53, vcc
	v_lshlrev_b32_e32 v53, 2, v53
	ds_bpermute_b32 v71, v53, v70
	s_and_saveexec_b64 s[78:79], s[10:11]
	s_cbranch_execz .LBB0_325
	v_ashrrev_i32_e32 v53, 31, v52
	v_lshlrev_b64 v[72:73], 5, v[52:53]
	v_lshl_add_u64 v[72:73], s[64:65], 0, v[72:73]
	s_lshl_b32 s24, s69, 2
	v_lshl_add_u64 v[72:73], v[72:73], 0, s[24:25]
	s_lshl_b32 s24, s21, 2
	v_lshl_add_u64 v[72:73], v[72:73], 0, s[24:25]
	s_waitcnt lgkmcnt(0)
	v_add_f32_e32 v53, v70, v71
	global_store_dword v[72:73], v53, off

.LBB0_333:
	s_waitcnt lgkmcnt(0)
	v_pk_mul_f32 v[16:17], v[16:17], v[34:35] op_sel_hi:[1,0]
	v_pk_mul_f32 v[18:19], v[18:19], v[34:35] op_sel_hi:[1,0]
	v_pk_mul_f32 v[12:13], v[12:13], v[34:35] op_sel_hi:[1,0]
	v_pk_mul_f32 v[14:15], v[14:15], v[34:35] op_sel_hi:[1,0]
	v_pk_mul_f32 v[8:9], v[8:9], v[34:35] op_sel_hi:[1,0]
	v_pk_mul_f32 v[10:11], v[10:11], v[34:35] op_sel_hi:[1,0]
	v_pk_mul_f32 v[4:5], v[4:5], v[34:35] op_sel_hi:[1,0]
	v_pk_mul_f32 v[6:7], v[6:7], v[34:35] op_sel_hi:[1,0]
	s_and_b64 vcc, exec, s[18:19]
	s_mov_b64 s[16:17], -1
	s_cbranch_vccnz .LBB0_340
	s_and_b64 vcc, exec, s[14:15]
	s_cbranch_vccz .Lp1_gelu_8
	v_mov_b64_e32 v[34:35], v[16:17]
	v_mov_b64_e32 v[40:41], v[18:19]
	v_mov_b64_e32 v[42:43], v[12:13]
	v_mov_b64_e32 v[44:45], v[14:15]
	v_mov_b64_e32 v[46:47], v[8:9]
	v_mov_b64_e32 v[48:49], v[10:11]
	v_mov_b64_e32 v[50:51], v[4:5]
	v_mov_b64_e32 v[52:53], v[6:7]
	s_branch .LBB0_339
.Lp1_gelu_8:
	v_mul_f32_e32 v33, 0x3d922279, v16
	v_fmaak_f32 v33, v16, v33, 0x3fcc422a
	v_mul_f32_e32 v34, 0x3d922279, v17
	v_mul_f32_e32 v33, v16, v33
	v_fmaak_f32 v34, v17, v34, 0x3fcc422a
	v_mul_f32_e32 v33, 0xbfb8aa3b, v33
	v_mul_f32_e32 v34, v17, v34
	v_exp_f32_e32 v33, v33
	v_mul_f32_e32 v34, 0xbfb8aa3b, v34
	v_exp_f32_e32 v35, v34
	v_mul_f32_e32 v40, 0x3d922279, v19
	v_add_f32_e32 v33, 1.0, v33
	v_rcp_f32_e32 v34, v33
	v_add_f32_e32 v33, 1.0, v35
	v_rcp_f32_e32 v35, v33
	v_mul_f32_e32 v33, 0x3d922279, v18
	v_fmaak_f32 v33, v18, v33, 0x3fcc422a
	v_mul_f32_e32 v33, v18, v33
	v_fmaak_f32 v40, v19, v40, 0x3fcc422a
	v_mul_f32_e32 v33, 0xbfb8aa3b, v33
	v_mul_f32_e32 v40, v19, v40
	v_exp_f32_e32 v33, v33
	v_mul_f32_e32 v40, 0xbfb8aa3b, v40
	v_exp_f32_e32 v41, v40
	v_mul_f32_e32 v42, 0x3d922279, v13
	v_add_f32_e32 v33, 1.0, v33
	v_rcp_f32_e32 v40, v33
	v_add_f32_e32 v33, 1.0, v41
	v_rcp_f32_e32 v41, v33
	v_mul_f32_e32 v33, 0x3d922279, v12
	v_fmaak_f32 v33, v12, v33, 0x3fcc422a
	v_mul_f32_e32 v33, v12, v33
	v_fmaak_f32 v42, v13, v42, 0x3fcc422a
	v_mul_f32_e32 v33, 0xbfb8aa3b, v33
	v_mul_f32_e32 v42, v13, v42
	v_exp_f32_e32 v33, v33
	v_mul_f32_e32 v42, 0xbfb8aa3b, v42
	v_exp_f32_e32 v43, v42
	v_mul_f32_e32 v44, 0x3d922279, v15
	v_add_f32_e32 v33, 1.0, v33
	v_rcp_f32_e32 v42, v33
	v_add_f32_e32 v33, 1.0, v43
	v_rcp_f32_e32 v43, v33
	v_mul_f32_e32 v33, 0x3d922279, v14
	v_fmaak_f32 v33, v14, v33, 0x3fcc422a
	v_mul_f32_e32 v33, v14, v33
	v_fmaak_f32 v44, v15, v44, 0x3fcc422a
	v_mul_f32_e32 v33, 0xbfb8aa3b, v33
	v_mul_f32_e32 v44, v15, v44
	v_exp_f32_e32 v33, v33
	v_mul_f32_e32 v44, 0xbfb8aa3b, v44
	v_exp_f32_e32 v45, v44
	v_mul_f32_e32 v46, 0x3d922279, v9
	v_add_f32_e32 v33, 1.0, v33
	v_rcp_f32_e32 v44, v33
	v_add_f32_e32 v33, 1.0, v45
	v_rcp_f32_e32 v45, v33
	v_mul_f32_e32 v33, 0x3d922279, v8
	v_fmaak_f32 v33, v8, v33, 0x3fcc422a
	v_mul_f32_e32 v33, v8, v33
	v_fmaak_f32 v46, v9, v46, 0x3fcc422a
	v_mul_f32_e32 v33, 0xbfb8aa3b, v33
	v_mul_f32_e32 v46, v9, v46
	v_exp_f32_e32 v33, v33
	v_mul_f32_e32 v46, 0xbfb8aa3b, v46
	v_exp_f32_e32 v47, v46
	v_mul_f32_e32 v48, 0x3d922279, v11
	v_add_f32_e32 v33, 1.0, v33
	v_rcp_f32_e32 v46, v33
	v_add_f32_e32 v33, 1.0, v47
	v_rcp_f32_e32 v47, v33
	v_mul_f32_e32 v33, 0x3d922279, v10
	v_fmaak_f32 v33, v10, v33, 0x3fcc422a
	v_mul_f32_e32 v33, v10, v33
	v_fmaak_f32 v48, v11, v48, 0x3fcc422a
	v_mul_f32_e32 v33, 0xbfb8aa3b, v33
	v_mul_f32_e32 v48, v11, v48
	v_exp_f32_e32 v33, v33
	v_mul_f32_e32 v48, 0xbfb8aa3b, v48
	v_exp_f32_e32 v49, v48
	v_mul_f32_e32 v50, 0x3d922279, v5
	v_add_f32_e32 v33, 1.0, v33
	v_rcp_f32_e32 v48, v33
	v_add_f32_e32 v33, 1.0, v49
	v_rcp_f32_e32 v49, v33
	v_mul_f32_e32 v33, 0x3d922279, v4
	v_fmaak_f32 v33, v4, v33, 0x3fcc422a
	v_mul_f32_e32 v33, v4, v33
	v_fmaak_f32 v50, v5, v50, 0x3fcc422a
	v_mul_f32_e32 v33, 0xbfb8aa3b, v33
	v_mul_f32_e32 v50, v5, v50
	v_exp_f32_e32 v33, v33
	v_mul_f32_e32 v50, 0xbfb8aa3b, v50
	v_exp_f32_e32 v51, v50
	v_mul_f32_e32 v52, 0x3d922279, v7
	v_add_f32_e32 v33, 1.0, v33
	v_rcp_f32_e32 v50, v33
	v_add_f32_e32 v33, 1.0, v51
	v_rcp_f32_e32 v51, v33
	v_mul_f32_e32 v33, 0x3d922279, v6
	v_fmaak_f32 v33, v6, v33, 0x3fcc422a
	v_mul_f32_e32 v33, v6, v33
	v_fmaak_f32 v52, v7, v52, 0x3fcc422a
	v_mul_f32_e32 v33, 0xbfb8aa3b, v33
	v_mul_f32_e32 v52, v7, v52
	v_exp_f32_e32 v33, v33
	v_mul_f32_e32 v52, 0xbfb8aa3b, v52
	v_exp_f32_e32 v53, v52
	v_pk_mul_f32 v[34:35], v[16:17], v[34:35]
	v_add_f32_e32 v33, 1.0, v33
	v_rcp_f32_e32 v52, v33
	v_add_f32_e32 v33, 1.0, v53
	v_rcp_f32_e32 v53, v33
	v_pk_mul_f32 v[40:41], v[18:19], v[40:41]
	v_pk_mul_f32 v[42:43], v[12:13], v[42:43]
	v_pk_mul_f32 v[44:45], v[14:15], v[44:45]
	v_pk_mul_f32 v[46:47], v[8:9], v[46:47]
	v_pk_mul_f32 v[48:49], v[10:11], v[48:49]
	v_pk_mul_f32 v[50:51], v[4:5], v[50:51]
	s_andn2_b64 vcc, exec, s[76:77]
	v_pk_mul_f32 v[52:53], v[6:7], v[52:53]
	s_cbranch_vccnz .LBB0_339
	v_pk_mul_f32 v[54:55], v[34:35], v[34:35]
	v_pk_mul_f32 v[56:57], v[40:41], v[40:41]
	v_add_f32_e32 v33, v54, v55
	v_add_f32_e32 v33, v56, v33
	v_pk_mul_f32 v[58:59], v[42:43], v[42:43]
	v_add_f32_e32 v33, v57, v33
	v_add_f32_e32 v33, v58, v33
	v_pk_mul_f32 v[60:61], v[44:45], v[44:45]
	v_add_f32_e32 v33, v59, v33
	v_add_f32_e32 v33, v60, v33
	v_pk_mul_f32 v[62:63], v[46:47], v[46:47]
	v_add_f32_e32 v33, v61, v33
	v_add_f32_e32 v33, v62, v33
	v_pk_mul_f32 v[64:65], v[48:49], v[48:49]
	v_add_f32_e32 v33, v63, v33
	v_add_f32_e32 v33, v64, v33
	v_mbcnt_hi_u32_b32 v55, -1, v1
	v_pk_mul_f32 v[66:67], v[50:51], v[50:51]
	v_add_f32_e32 v33, v65, v33
	v_and_b32_e32 v56, 64, v55
	v_add_f32_e32 v33, v66, v33
	v_xor_b32_e32 v54, 16, v55
	v_add_u32_e32 v56, 64, v56
	v_pk_mul_f32 v[68:69], v[52:53], v[52:53]
	v_add_f32_e32 v33, v67, v33
	v_cmp_lt_i32_e32 vcc, v54, v56
	v_add_f32_e32 v33, v68, v33
	v_add_f32_e32 v33, v69, v33
	v_cndmask_b32_e32 v54, v55, v54, vcc
	v_lshlrev_b32_e32 v54, 2, v54
	ds_bpermute_b32 v54, v54, v33
	s_waitcnt lgkmcnt(0)
	v_add_f32_e32 v54, v33, v54
	v_xor_b32_e32 v33, 32, v55
	v_cmp_lt_i32_e32 vcc, v33, v56
	s_nop 1
	v_cndmask_b32_e32 v33, v55, v33, vcc
	v_lshlrev_b32_e32 v33, 2, v33
	ds_bpermute_b32 v55, v33, v54
	s_and_saveexec_b64 s[14:15], s[10:11]
	s_cbranch_execz .LBB0_338
	v_ashrrev_i32_e32 v33, 31, v32
	v_lshlrev_b64 v[56:57], 5, v[32:33]
	v_lshl_add_u64 v[56:57], s[64:65], 0, v[56:57]
	s_lshl_b32 s24, s69, 2
	v_lshl_add_u64 v[56:57], v[56:57], 0, s[24:25]
	s_lshl_b32 s24, s21, 2
	v_lshl_add_u64 v[56:57], v[56:57], 0, s[24:25]
	s_waitcnt lgkmcnt(0)
	v_add_f32_e32 v33, v54, v55
	global_store_dword v[56:57], v33, off
